# conv+pool tile fills batched, lean grid barrier, pipelined EpiGate epilogue, P4 zero-K-step skip (robust to multi-tile workgroups)
# speedup vs baseline: 1.0023x; 1.0023x over previous
; template <class Epi>
; __device__ __forceinline__ void gemm_phase(LAS unsigned char* lds, const Gemm g, const StaticOrder& S, const Epi& E, const int tid) {
;     ...
;         const bool has_next = S.next(ui + 1, nxt);
;         const char* nA = has_next ? (const char*)g.A + (size_t)nxt.pm * tstepA : cA; const char* nB = has_next ? (const char*)g.Bt + (size_t)nxt.pn * tstepB : cB;
; __device__ __forceinline__ void acc_zero(AccMut acc) {
; #pragma unroll
;     for (int a = 0; a < 2; ++a)
; #pragma unroll
;         for (int b = 0; b < 2; ++b)
; #pragma unroll
;             for (int m = 0; m < 4; ++m)
; #pragma unroll
;                 for (int n = 0; n < 2; ++n) acc[a][b][m][n] = (f32x4){0.f, 0.f, 0.f, 0.f};
; }
.LBB0_660:
	s_ashr_i32 s15, s14, 31
	v_cmp_lt_i64_e32 vcc, s[4:5], v[194:195]
	s_lshl_b64 s[4:5], s[14:15], 19
	s_add_u32 s16, s27, s4
	s_addc_u32 s17, s28, s5
	s_lshl_b32 s100, s12, 9
	s_add_u32 s16, s16, s100
	s_addc_u32 s17, s17, 0
	s_and_b64 s[4:5], vcc, exec
	s_cselect_b32 s4, s17, s21
	s_cselect_b32 s5, s16, s20
	s_ashr_i32 s13, s12, 31
	s_lshl_b64 s[18:19], s[12:13], 19
	s_add_u32 s18, s3, s18
	s_addc_u32 s19, s26, s19
	s_add_u32 s18, s18, s100
	s_addc_u32 s19, s19, 0
	s_and_b64 s[24:25], vcc, exec
	s_cselect_b32 s13, s19, s23
	s_cselect_b32 s15, s18, s22
	s_add_u32 s20, s20, 0x40080
	s_addc_u32 s21, s21, 0
	s_add_u32 s41, s22, 0x100
	v_mov_b32_e32 v0, 0
	s_addc_u32 s42, s23, 0
	s_mov_b32 s43, -2
	v_mov_b32_e32 v1, v0
	v_mov_b32_e32 v2, v0
	v_mov_b32_e32 v3, v0
	v_mov_b32_e32 v4, v0
	v_mov_b32_e32 v5, v0
	v_mov_b32_e32 v6, v0
	v_mov_b32_e32 v7, v0
	v_mov_b32_e32 v16, v0
	v_mov_b32_e32 v17, v0
	v_mov_b32_e32 v18, v0
	v_mov_b32_e32 v19, v0
	v_mov_b32_e32 v20, v0
	v_mov_b32_e32 v21, v0
	v_mov_b32_e32 v22, v0
	v_mov_b32_e32 v23, v0
	v_mov_b32_e32 v32, v0
	v_mov_b32_e32 v33, v0
	v_mov_b32_e32 v34, v0
	v_mov_b32_e32 v35, v0
	v_mov_b32_e32 v36, v0
	v_mov_b32_e32 v37, v0
	v_mov_b32_e32 v38, v0
	v_mov_b32_e32 v39, v0
	v_mov_b32_e32 v48, v0
	v_mov_b32_e32 v49, v0
	v_mov_b32_e32 v50, v0
	v_mov_b32_e32 v51, v0
	v_mov_b32_e32 v52, v0
	v_mov_b32_e32 v53, v0
	v_mov_b32_e32 v54, v0
	v_mov_b32_e32 v55, v0
	v_mov_b32_e32 v8, v0
	v_mov_b32_e32 v9, v0
	v_mov_b32_e32 v10, v0
	v_mov_b32_e32 v11, v0
	v_mov_b32_e32 v12, v0
	v_mov_b32_e32 v13, v0
	v_mov_b32_e32 v14, v0
	v_mov_b32_e32 v15, v0
	v_mov_b32_e32 v24, v0
	v_mov_b32_e32 v25, v0
	v_mov_b32_e32 v26, v0
	v_mov_b32_e32 v27, v0
	v_mov_b32_e32 v28, v0
	v_mov_b32_e32 v29, v0
	v_mov_b32_e32 v30, v0
	v_mov_b32_e32 v31, v0
	v_mov_b32_e32 v40, v0
	v_mov_b32_e32 v41, v0
	v_mov_b32_e32 v42, v0
	v_mov_b32_e32 v43, v0
	v_mov_b32_e32 v44, v0
	v_mov_b32_e32 v45, v0
	v_mov_b32_e32 v46, v0
	v_mov_b32_e32 v47, v0
	v_mov_b32_e32 v56, v0
	v_mov_b32_e32 v57, v0
	v_mov_b32_e32 v58, v0
	v_mov_b32_e32 v59, v0
	v_mov_b32_e32 v60, v0
	v_mov_b32_e32 v61, v0
	v_mov_b32_e32 v62, v0
	v_mov_b32_e32 v63, v0
	v_mov_b32_e32 v64, v0
	v_mov_b32_e32 v65, v0
	v_mov_b32_e32 v66, v0
	v_mov_b32_e32 v67, v0
	v_mov_b32_e32 v68, v0
	v_mov_b32_e32 v69, v0
	v_mov_b32_e32 v70, v0
	v_mov_b32_e32 v71, v0
	v_mov_b32_e32 v80, v0
	v_mov_b32_e32 v81, v0
	v_mov_b32_e32 v82, v0
	v_mov_b32_e32 v83, v0
	v_mov_b32_e32 v84, v0
	v_mov_b32_e32 v85, v0
	v_mov_b32_e32 v86, v0
	v_mov_b32_e32 v87, v0
	v_mov_b32_e32 v96, v0
	v_mov_b32_e32 v97, v0
	v_mov_b32_e32 v98, v0
	v_mov_b32_e32 v99, v0
	v_mov_b32_e32 v100, v0
	v_mov_b32_e32 v101, v0
	v_mov_b32_e32 v102, v0
	v_mov_b32_e32 v103, v0
	v_mov_b32_e32 v112, v0
	v_mov_b32_e32 v113, v0
	v_mov_b32_e32 v114, v0
	v_mov_b32_e32 v115, v0
	v_mov_b32_e32 v116, v0
	v_mov_b32_e32 v117, v0
	v_mov_b32_e32 v118, v0
	v_mov_b32_e32 v119, v0
	v_mov_b32_e32 v72, v0
	v_mov_b32_e32 v73, v0
	v_mov_b32_e32 v74, v0
	v_mov_b32_e32 v75, v0
	v_mov_b32_e32 v76, v0
	v_mov_b32_e32 v77, v0
	v_mov_b32_e32 v78, v0
	v_mov_b32_e32 v79, v0
	v_mov_b32_e32 v88, v0
	v_mov_b32_e32 v89, v0
	v_mov_b32_e32 v90, v0
	v_mov_b32_e32 v91, v0
	v_mov_b32_e32 v92, v0
	v_mov_b32_e32 v93, v0
	v_mov_b32_e32 v94, v0
	v_mov_b32_e32 v95, v0
	v_mov_b32_e32 v104, v0
	v_mov_b32_e32 v105, v0
	v_mov_b32_e32 v106, v0
	v_mov_b32_e32 v107, v0
	v_mov_b32_e32 v108, v0
	v_mov_b32_e32 v109, v0
	v_mov_b32_e32 v110, v0
	v_mov_b32_e32 v111, v0
	v_mov_b32_e32 v120, v0
	v_mov_b32_e32 v121, v0
	v_mov_b32_e32 v122, v0
	v_mov_b32_e32 v123, v0
	v_mov_b32_e32 v124, v0
	v_mov_b32_e32 v125, v0
	v_mov_b32_e32 v126, v0
	v_mov_b32_e32 v127, v0

; __global__ void __launch_bounds__(512, 2) fwd_megakernel(Params p_) {
	.amdhsa_kernel _Z14fwd_megakernel6Params
		.amdhsa_group_segment_fixed_size 0
		.amdhsa_private_segment_fixed_size 0
		.amdhsa_kernarg_size 480
		.amdhsa_user_sgpr_count 2
		.amdhsa_user_sgpr_dispatch_ptr 0
		.amdhsa_user_sgpr_queue_ptr 0
		.amdhsa_user_sgpr_kernarg_segment_ptr 1
		.amdhsa_user_sgpr_dispatch_id 0
		.amdhsa_user_sgpr_kernarg_preload_length 0
		.amdhsa_user_sgpr_kernarg_preload_offset 0
		.amdhsa_user_sgpr_private_segment_size 0
		.amdhsa_uses_dynamic_stack 0
		.amdhsa_enable_private_segment 0
		.amdhsa_system_sgpr_workgroup_id_x 1
		.amdhsa_system_sgpr_workgroup_id_y 0
		.amdhsa_system_sgpr_workgroup_id_z 0
		.amdhsa_system_sgpr_workgroup_info 0
		.amdhsa_system_vgpr_workitem_id 2
		.amdhsa_next_free_vgpr 256
		.amdhsa_next_free_sgpr 102
		.amdhsa_accum_offset 256
		.amdhsa_reserve_vcc 1
		.amdhsa_float_round_mode_32 0
		.amdhsa_float_round_mode_16_64 0
		.amdhsa_float_denorm_mode_32 3
		.amdhsa_float_denorm_mode_16_64 3
		.amdhsa_dx10_clamp 1
		.amdhsa_ieee_mode 1
		.amdhsa_fp16_overflow 0
		.amdhsa_tg_split 0
		.amdhsa_exception_fp_ieee_invalid_op 0
		.amdhsa_exception_fp_denorm_src 0
		.amdhsa_exception_fp_ieee_div_zero 0
		.amdhsa_exception_fp_ieee_overflow 0
		.amdhsa_exception_fp_ieee_underflow 0
		.amdhsa_exception_fp_ieee_inexact 0
		.amdhsa_exception_int_div_zero 0
	.end_amdhsa_kernel

; __global__ void __launch_bounds__(512, 2) fwd_megakernel(Params p_) {
amdhsa.kernels:
  - .agpr_count:     0
    .args:
      - .offset:         0
        .size:           224
        .value_kind:     by_value
      - .offset:         224
        .size:           4
        .value_kind:     hidden_block_count_x
      - .offset:         228
        .size:           4
        .value_kind:     hidden_block_count_y
      - .offset:         232
        .size:           4
        .value_kind:     hidden_block_count_z
      - .offset:         236
        .size:           2
        .value_kind:     hidden_group_size_x
      - .offset:         238
        .size:           2
        .value_kind:     hidden_group_size_y
      - .offset:         240
        .size:           2
        .value_kind:     hidden_group_size_z
      - .offset:         242
        .size:           2
        .value_kind:     hidden_remainder_x
      - .offset:         244
        .size:           2
        .value_kind:     hidden_remainder_y
      - .offset:         246
        .size:           2
        .value_kind:     hidden_remainder_z
      - .offset:         264
        .size:           8
        .value_kind:     hidden_global_offset_x
      - .offset:         272
        .size:           8
        .value_kind:     hidden_global_offset_y
      - .offset:         280
        .size:           8
        .value_kind:     hidden_global_offset_z
      - .offset:         288
        .size:           2
        .value_kind:     hidden_grid_dims
      - .offset:         312
        .size:           8
        .value_kind:     hidden_multigrid_sync_arg
      - .offset:         344
        .size:           4
        .value_kind:     hidden_dynamic_lds_size
    .group_segment_fixed_size: 0
    .kernarg_segment_align: 8
    .kernarg_segment_size: 480
    .language:       OpenCL C
    .language_version:
      - 2
      - 0
    .max_flat_workgroup_size: 512
    .name:           _Z14fwd_megakernel6Params
    .private_segment_fixed_size: 0
    .sgpr_count:     108
    .sgpr_spill_count: 171
    .symbol:         _Z14fwd_megakernel6Params.kd
    .uniform_work_group_size: 1
    .uses_dynamic_stack: false
    .vgpr_count:     256
    .vgpr_spill_count: 0
    .wavefront_size: 64
